# baseline (speedup 1.0000x reference)
; __device__ __forceinline__ void final_phase(float* out, const bf16_t* HB, const unsigned long long* ss, const float* fw) {
;     int tid_ = threadIdx.x; asm volatile("" : "+v"(tid_)); const int lane = tid_ & 63, w = tid_ >> 6;
;     for (int r = blockIdx.x * 8 + w; r < NREAL; r += gridDim.x * 8) {
;         const float rstd = __builtin_amdgcn_rsqf((float)ss[r] * (1.f / 16777216.f) * (1.f / 2048.f) + 1e-6f);
; #pragma unroll
;         for (int i = 0; i < 4; ++i) {
;             const int c = 8 * lane + 512 * i;
;             const u32x4 hv = *(const u32x4*)(HB + (size_t)r * 2048 + c);
;             float f[8]; unpack8(hv, f);
;             const f32x4 g0 = *(const f32x4*)(fw + c), g1 = *(const f32x4*)(fw + c + 4);
;             f32x4 o0, o1;
; #pragma unroll
;             for (int j = 0; j < 4; ++j) { o0[j] = f[j] * rstd * g0[j]; o1[j] = f[4 + j] * rstd * g1[j]; }
;             *(f32x4*)(out + (size_t)r * 2048 + c) = o0; *(f32x4*)(out + (size_t)r * 2048 + c + 4) = o1;
;         }
;     }
; }
.LBB0_119:
	v_ashrrev_i32_e32 v1, 31, v0
	v_lshl_add_u64 v[14:15], v[0:1], 3, s[70:71]
	global_load_dwordx2 v[26:27], v[14:15], off
	v_lshlrev_b64 v[14:15], 12, v[0:1]
	v_lshl_add_u64 v[28:29], v[8:9], 0, v[14:15]
	global_load_dwordx4 v[14:17], v[28:29], off nt
	global_load_dwordx4 v[18:21], v[2:3], off
	global_load_dwordx4 v[22:25], v[2:3], off offset:16
	v_lshlrev_b64 v[30:31], 13, v[0:1]
	v_lshl_add_u64 v[30:31], s[66:67], 0, v[30:31]
	v_lshl_add_u64 v[32:33], v[30:31], 0, v[188:189]
	v_mov_b32_e32 v13, v189
	v_add_u32_e32 v0, s3, v0
	v_cmp_lt_i32_e32 vcc, s94, v0
	s_or_b64 s[4:5], vcc, s[4:5]
	s_waitcnt vmcnt(3)
	v_ffbh_u32_e32 v1, v27
	v_min_u32_e32 v1, 32, v1
	v_lshlrev_b64 v[26:27], v1, v[26:27]
	v_min_u32_e32 v11, 1, v26
	v_or_b32_e32 v11, v27, v11
	v_cvt_f32_u32_e32 v11, v11
	v_sub_u32_e32 v1, 32, v1
	s_waitcnt vmcnt(2)
	v_lshlrev_b32_e32 v34, 16, v14
	v_and_b32_e32 v35, 0xffff0000, v14
	v_ldexp_f32 v1, v11, v1
	v_mul_f32_e32 v1, 0x33800000, v1
	v_fmamk_f32 v1, v1, 0x3a000000, v227
	v_rsq_f32_e32 v26, v1
	v_lshlrev_b32_e32 v14, 16, v15
	v_and_b32_e32 v15, 0xffff0000, v15
	v_lshlrev_b32_e32 v36, 16, v16
	v_and_b32_e32 v37, 0xffff0000, v16
	v_lshlrev_b32_e32 v16, 16, v17
	v_and_b32_e32 v17, 0xffff0000, v17
	v_pk_mul_f32 v[34:35], v[26:27], v[34:35] op_sel_hi:[0,1]
	v_pk_mul_f32 v[38:39], v[26:27], v[14:15] op_sel_hi:[0,1]
	v_pk_mul_f32 v[36:37], v[26:27], v[36:37] op_sel_hi:[0,1]
	v_pk_mul_f32 v[40:41], v[26:27], v[16:17] op_sel_hi:[0,1]
	s_waitcnt vmcnt(1)
	v_pk_mul_f32 v[14:15], v[18:19], v[34:35]
	v_pk_mul_f32 v[16:17], v[20:21], v[38:39]
	s_waitcnt vmcnt(0)
	v_pk_mul_f32 v[18:19], v[22:23], v[36:37]
	v_pk_mul_f32 v[20:21], v[24:25], v[40:41]
	global_store_dwordx4 v[32:33], v[14:17], off nt
	global_store_dwordx4 v[32:33], v[18:21], off offset:16 nt
	global_load_dwordx4 v[14:17], v[28:29], off offset:1024 nt
	s_nop 0
	global_load_dwordx4 v[18:21], v[2:3], off offset:2048
	global_load_dwordx4 v[22:25], v[2:3], off offset:2064
	v_mov_b32_e32 v11, v189
	s_waitcnt vmcnt(2)
	v_lshlrev_b32_e32 v34, 16, v14
	v_and_b32_e32 v35, 0xffff0000, v14
	v_lshlrev_b32_e32 v14, 16, v15
	v_and_b32_e32 v15, 0xffff0000, v15
	v_lshlrev_b32_e32 v36, 16, v16
	v_and_b32_e32 v37, 0xffff0000, v16
	v_lshlrev_b32_e32 v16, 16, v17
	v_and_b32_e32 v17, 0xffff0000, v17
	v_pk_mul_f32 v[34:35], v[26:27], v[34:35] op_sel_hi:[0,1]
	v_pk_mul_f32 v[38:39], v[26:27], v[14:15] op_sel_hi:[0,1]
	v_pk_mul_f32 v[36:37], v[26:27], v[36:37] op_sel_hi:[0,1]
	v_pk_mul_f32 v[40:41], v[26:27], v[16:17] op_sel_hi:[0,1]
	s_waitcnt vmcnt(1)
	v_pk_mul_f32 v[14:15], v[18:19], v[34:35]
	v_pk_mul_f32 v[16:17], v[20:21], v[38:39]
	s_waitcnt vmcnt(0)
	v_pk_mul_f32 v[18:19], v[22:23], v[36:37]
	v_pk_mul_f32 v[20:21], v[24:25], v[40:41]
	global_store_dwordx4 v[32:33], v[14:17], off offset:2048 nt
	global_store_dwordx4 v[32:33], v[18:21], off offset:2064 nt
	global_load_dwordx4 v[14:17], v[28:29], off offset:2048 nt
	s_nop 0
	global_load_dwordx4 v[18:21], v[4:5], off
	global_load_dwordx4 v[22:25], v[4:5], off offset:16
	v_lshl_add_u64 v[32:33], v[30:31], 0, v[10:11]
	s_waitcnt vmcnt(2)
	v_lshlrev_b32_e32 v34, 16, v14
	v_and_b32_e32 v35, 0xffff0000, v14
	v_lshlrev_b32_e32 v14, 16, v15
	v_and_b32_e32 v15, 0xffff0000, v15
	v_lshlrev_b32_e32 v36, 16, v16
	v_and_b32_e32 v37, 0xffff0000, v16
	v_lshlrev_b32_e32 v16, 16, v17
	v_and_b32_e32 v17, 0xffff0000, v17
	v_pk_mul_f32 v[34:35], v[26:27], v[34:35] op_sel_hi:[0,1]
	v_pk_mul_f32 v[38:39], v[26:27], v[14:15] op_sel_hi:[0,1]
	v_pk_mul_f32 v[36:37], v[26:27], v[36:37] op_sel_hi:[0,1]
	v_pk_mul_f32 v[40:41], v[26:27], v[16:17] op_sel_hi:[0,1]
	s_waitcnt vmcnt(1)
	v_pk_mul_f32 v[14:15], v[18:19], v[34:35]
	v_pk_mul_f32 v[16:17], v[20:21], v[38:39]
	s_waitcnt vmcnt(0)
	v_pk_mul_f32 v[18:19], v[22:23], v[36:37]
	v_pk_mul_f32 v[20:21], v[24:25], v[40:41]
	global_store_dwordx4 v[32:33], v[14:17], off nt
	global_store_dwordx4 v[32:33], v[18:21], off offset:16 nt
	global_load_dwordx4 v[14:17], v[28:29], off offset:3072 nt
	s_nop 0
	global_load_dwordx4 v[18:21], v[6:7], off
	global_load_dwordx4 v[22:25], v[6:7], off offset:16
	v_lshl_add_u64 v[28:29], v[30:31], 0, v[12:13]
	s_waitcnt vmcnt(2)
	v_lshlrev_b32_e32 v30, 16, v14
	v_and_b32_e32 v31, 0xffff0000, v14
	v_lshlrev_b32_e32 v14, 16, v15
	v_and_b32_e32 v15, 0xffff0000, v15
	v_lshlrev_b32_e32 v32, 16, v16
	v_and_b32_e32 v33, 0xffff0000, v16
	v_lshlrev_b32_e32 v16, 16, v17
	v_and_b32_e32 v17, 0xffff0000, v17
	v_pk_mul_f32 v[30:31], v[26:27], v[30:31] op_sel_hi:[0,1]
	v_pk_mul_f32 v[34:35], v[26:27], v[14:15] op_sel_hi:[0,1]
	v_pk_mul_f32 v[32:33], v[26:27], v[32:33] op_sel_hi:[0,1]
	v_pk_mul_f32 v[26:27], v[26:27], v[16:17] op_sel_hi:[0,1]
	s_waitcnt vmcnt(1)
	v_pk_mul_f32 v[14:15], v[18:19], v[30:31]
	v_pk_mul_f32 v[16:17], v[20:21], v[34:35]
	s_waitcnt vmcnt(0)
	v_pk_mul_f32 v[18:19], v[22:23], v[32:33]
	v_pk_mul_f32 v[20:21], v[24:25], v[26:27]
	global_store_dwordx4 v[28:29], v[14:17], off nt
	global_store_dwordx4 v[28:29], v[18:21], off offset:16 nt
	s_andn2_b64 exec, exec, s[4:5]
	s_cbranch_execnz .LBB0_119
